# ffn_conv: v-half loads hoisted above the u-load wait (one memory round trip per iteration instead of two); c3 next-job prefetch uses SGPR-base + 32-bit offset addressing (about 90 fewer VALU per job)
# baseline (speedup 1.0000x reference)
; #define LAS __attribute__((address_space(3)))
; __device__ __forceinline__ float bf2f(bf16_t b) { return __uint_as_float(((unsigned)b) << 16); }
; __device__ __forceinline__ bf16_t f2bf(float f) { return (bf16_t)(cvt_pk_bf16(f, 0.f) & 0xffffu); }
; __device__ __forceinline__ float rcpf_(float x) { return __builtin_amdgcn_rcpf(x); }
; __device__ __forceinline__ float sigm(float x) { return rcpf_(1.f + __expf(-x)); }
; __device__ __forceinline__ void phase_hgrn_c3(const Params& p, int l, int bid, int nblk, LAS unsigned char* lds) {
;     ...
;         for (int i = 0; i < 16; ++i) {
;             const float z = bf2f(fr_[i]);
;             const float sg1 = rcpf_(1.f + __expf(-z)), om = rcpf_(1.f + __expf(z));
;             const float f = lb + (1.f - lb) * sg1; run += fmaxf(__logf(f), -60.f); bl[i] = run; kk[i] = (1.f - lb) * om;
;         }
;         gsum[sg * 128 + k] = run;
; #pragma unroll
;         for (int i = 0; i < 4; ++i) { const int id = tid + 512 * i, vd = id >> 4, k8 = (id & 15) * 8; *(LAS u32x4*)(S0T + vd * 136 + k8) = s0v[i]; }
; #pragma unroll
;         for (int i = 0; i < 2; ++i) {
;             const int id = tid + 512 * i, s = id & 63, v8 = (id >> 6) * 8;
; #pragma unroll
;             for (int e = 0; e < 8; ++e) vT[(v8 + e) * 72 + s] = (bf16_t)vf_[i][e];
;         }
;         __syncthreads();
;         float off = 0.f;
; #pragma unroll
;         for (int q = 0; q < 4; ++q) { if (q < sg) off += gsum[q * 128 + k]; }
;         const float mref = gsum[k] + gsum[128 + k];
; #pragma unroll
;         for (int i = 0; i < 16; ++i) {
;             const int s = 16 * sg + i; const float bt = bl[i] + off;
;             const float qr = bf2f(qr_[i]); const float q = qr * sigm(qr);
;             const float dA = fminf(fmaxf(bt - mref, -60.f), 60.f);
;             qA[s * 136 + k] = f2bf(q * __expf(dA)); qB[s * 136 + k] = f2bf(q * __expf(bt)); kh[s * 136 + k] = f2bf(kk[i] * __expf(-dA));
;         }
.LBB0_243:
	s_or_b64 exec, exec, s[38:39]
	v_mul_f32_e32 v156, 0x3fb8aa3b, v156
	v_exp_f32_e32 v156, v156
	v_mul_f32_e32 v150, 0x3fb8aa3b, v150
	v_mul_f32_e32 v151, 0x3fb8aa3b, v151
	v_exp_f32_e32 v150, v150
	v_add_f32_e32 v156, 1.0, v156
	v_rcp_f32_e32 v164, v156
	v_mul_f32_e32 v156, 0x3fb8aa3b, v157
	v_exp_f32_e32 v156, v156
	v_exp_f32_e32 v151, v151
	v_mul_f32_e32 v152, 0x3fb8aa3b, v152
	v_mul_f32_e32 v148, 0x3fb8aa3b, v148
	v_add_f32_e32 v156, 1.0, v156
	v_rcp_f32_e32 v165, v156
	v_mul_f32_e32 v156, 0x3fb8aa3b, v158
	v_exp_f32_e32 v156, v156
	v_add_f32_e32 v150, 1.0, v150
	v_add_f32_e32 v151, 1.0, v151
	v_exp_f32_e32 v152, v152
	v_add_f32_e32 v156, 1.0, v156
	v_rcp_f32_e32 v166, v156
	v_mul_f32_e32 v156, 0x3fb8aa3b, v159
	v_exp_f32_e32 v156, v156
	v_exp_f32_e32 v148, v148
	v_rcp_f32_e32 v150, v150
	v_rcp_f32_e32 v151, v151
	v_add_f32_e32 v156, 1.0, v156
	v_rcp_f32_e32 v159, v156
	v_mul_f32_e32 v156, 0x3fb8aa3b, v160
	v_exp_f32_e32 v156, v156
	v_add_f32_e32 v152, 1.0, v152
	v_add_f32_e32 v148, 1.0, v148
	v_rcp_f32_e32 v152, v152
	v_add_f32_e32 v156, 1.0, v156
	v_rcp_f32_e32 v160, v156
	v_mul_f32_e32 v156, 0x3fb8aa3b, v161
	v_exp_f32_e32 v156, v156
	v_mul_f32_e32 v169, v150, v27
	v_mul_f32_e32 v170, v151, v27
	v_mul_f32_e32 v151, v160, v27
	v_add_f32_e32 v156, 1.0, v156
	v_rcp_f32_e32 v161, v156
	v_rcp_f32_e32 v148, v148
	v_mul_f32_e32 v171, v152, v27
	v_mul_f32_e32 v152, v159, v27
	v_mul_f32_e32 v150, v161, v27
	ds_read2st64_b32 v[160:161], v98 offset1:2
	v_lshlrev_b32_e32 v159, 16, v74
	v_mul_f32_e32 v167, v148, v27
	v_add_f32_e32 v28, v28, v26
	v_mul_f32_e32 v149, 0x3fb8aa3b, v149
	s_waitcnt lgkmcnt(0)
	v_add_f32_e32 v148, v160, v161
	v_mul_f32_e32 v160, 0xbfb8aa3b, v159
	v_exp_f32_e32 v160, v160
	v_exp_f32_e32 v149, v149
	v_mul_f32_e32 v153, 0x3fb8aa3b, v153
	v_exp_f32_e32 v153, v153
	v_add_f32_e32 v160, 1.0, v160
	v_rcp_f32_e32 v160, v160
	v_add_f32_e32 v149, 1.0, v149
	v_rcp_f32_e32 v149, v149
	v_add_f32_e32 v153, 1.0, v153
	v_mul_f32_e32 v159, v160, v159
	v_sub_f32_e32 v160, v28, v148
	v_mul_f32_e32 v28, 0x3fb8aa3b, v28
	v_exp_f32_e32 v28, v28
	v_med3_f32 v160, v160, s33, v243
	v_mul_f32_e32 v161, 0x3fb8aa3b, v160
	v_exp_f32_e32 v161, v161
	v_mul_f32_e32 v28, v159, v28
	v_cvt_pk_bf16_f32 v28, v28, v5
	ds_write_b16 v107, v28 offset:17408
	v_mul_f32_e32 v28, 0xbfb8aa3b, v160
	v_exp_f32_e32 v28, v28
	v_mul_f32_e32 v161, v159, v161
	v_mul_f32_e32 v168, v149, v27
	v_rcp_f32_e32 v153, v153
	v_mul_f32_e32 v28, v167, v28
	v_cvt_pk_bf16_f32 v28, v28, v5
	ds_write_b16 v107, v28 offset:34816
	v_add_f32_e32 v28, v31, v26
	v_lshlrev_b32_e32 v31, 16, v73
	v_mul_f32_e32 v159, 0xbfb8aa3b, v31
	v_exp_f32_e32 v159, v159
	v_mul_f32_e32 v158, v153, v27
	v_mul_f32_e32 v154, 0x3fb8aa3b, v154
	v_exp_f32_e32 v154, v154
	v_add_f32_e32 v159, 1.0, v159
	v_rcp_f32_e32 v159, v159
	v_mul_f32_e32 v156, 0x3fb8aa3b, v162
	v_add_f32_e32 v154, 1.0, v154
	v_rcp_f32_e32 v154, v154
	v_mul_f32_e32 v31, v159, v31
	v_sub_f32_e32 v159, v28, v148
	v_mul_f32_e32 v28, 0x3fb8aa3b, v28
	v_exp_f32_e32 v28, v28
	v_med3_f32 v159, v159, s33, v243
	v_mul_f32_e32 v160, 0x3fb8aa3b, v159
	v_exp_f32_e32 v160, v160
	v_mul_f32_e32 v28, v31, v28
	v_cvt_pk_bf16_f32 v28, v28, v5
	ds_write_b16 v107, v28 offset:17680
	v_mul_f32_e32 v28, 0xbfb8aa3b, v159
	v_exp_f32_e32 v28, v28
	v_mul_f32_e32 v160, v31, v160
	v_mul_f32_e32 v157, v154, v27
	v_exp_f32_e32 v156, v156
	v_mul_f32_e32 v28, v168, v28
	v_cvt_pk_bf16_f32 v28, v28, v5
	ds_write_b16 v107, v28 offset:35088
	v_add_f32_e32 v28, v29, v26
	v_lshlrev_b32_e32 v29, 16, v71
	v_mul_f32_e32 v31, 0xbfb8aa3b, v29
	v_exp_f32_e32 v31, v31
	v_mul_f32_e32 v155, 0x3fb8aa3b, v155
	v_exp_f32_e32 v155, v155
	v_add_f32_e32 v156, 1.0, v156
	v_add_f32_e32 v31, 1.0, v31
	v_rcp_f32_e32 v31, v31
	v_rcp_f32_e32 v162, v156
	v_mul_f32_e32 v156, 0x3fb8aa3b, v163
	v_add_f32_e32 v155, 1.0, v155
	v_mul_f32_e32 v29, v31, v29
	v_sub_f32_e32 v31, v28, v148
	v_med3_f32 v31, v31, s33, v243
	v_mul_f32_e32 v28, 0x3fb8aa3b, v28
	v_mul_f32_e32 v159, 0x3fb8aa3b, v31
	v_exp_f32_e32 v28, v28
	v_exp_f32_e32 v159, v159
	v_exp_f32_e32 v156, v156
	v_rcp_f32_e32 v155, v155
	v_mul_f32_e32 v28, v29, v28
	v_mul_f32_e32 v159, v29, v159
	v_cvt_pk_bf16_f32 v28, v28, v5
	v_lshlrev_b32_e32 v29, 16, v70
	ds_write_b16 v107, v28 offset:17952
	v_mul_f32_e32 v28, 0xbfb8aa3b, v31
	v_mul_f32_e32 v31, 0xbfb8aa3b, v29
	v_exp_f32_e32 v31, v31
	v_exp_f32_e32 v28, v28
	v_add_f32_e32 v156, 1.0, v156
	v_rcp_f32_e32 v163, v156
	v_add_f32_e32 v31, 1.0, v31
	v_rcp_f32_e32 v31, v31
	v_mul_f32_e32 v28, v169, v28
	v_cvt_pk_bf16_f32 v28, v28, v5
	ds_write_b16 v107, v28 offset:35360
	v_add_f32_e32 v28, v33, v26
	v_mul_f32_e32 v29, v31, v29
	v_sub_f32_e32 v31, v28, v148
	v_mul_f32_e32 v28, 0x3fb8aa3b, v28
	v_exp_f32_e32 v28, v28
	v_med3_f32 v31, v31, s33, v243
	v_mul_f32_e32 v33, 0x3fb8aa3b, v31
	v_exp_f32_e32 v33, v33
	v_mul_f32_e32 v28, v29, v28
	v_cvt_pk_bf16_f32 v28, v28, v5
	ds_write_b16 v107, v28 offset:18224
	v_mul_f32_e32 v28, 0xbfb8aa3b, v31
	v_exp_f32_e32 v28, v28
	v_mul_f32_e32 v33, v29, v33
	v_lshlrev_b32_e32 v29, 16, v82
	v_mul_f32_e32 v156, v155, v27
	v_mul_f32_e32 v28, v170, v28
	v_cvt_pk_bf16_f32 v28, v28, v5
	ds_write_b16 v107, v28 offset:35632
	v_add_f32_e32 v28, v30, v26
	v_mul_f32_e32 v30, 0xbfb8aa3b, v29
	v_exp_f32_e32 v30, v30
	v_mul_f32_e32 v155, v164, v27
	v_mul_f32_e32 v154, v165, v27
	v_mul_f32_e32 v153, v166, v27
	v_add_f32_e32 v30, 1.0, v30
	v_rcp_f32_e32 v30, v30
	v_mul_f32_e32 v149, v162, v27
	v_mul_f32_e32 v27, v163, v27
	s_cmpk_gt_i32 s46, 0x83f
	v_mul_f32_e32 v29, v30, v29
	v_sub_f32_e32 v30, v28, v148
	v_med3_f32 v30, v30, s33, v243
	v_mul_f32_e32 v28, 0x3fb8aa3b, v28
; __device__ __forceinline__ float bf2f(bf16_t b) { return __uint_as_float(((unsigned)b) << 16); }
; __device__ __forceinline__ bf16_t f2bf(float f) { return (bf16_t)(cvt_pk_bf16(f, 0.f) & 0xffffu); }
; __device__ __forceinline__ float sigm(float x) { return rcpf_(1.f + __expf(-x)); }
; __device__ __forceinline__ void phase_hgrn_c3(const Params& p, int l, int bid, int nblk, LAS unsigned char* lds) {
;     ...
;         const float mref = gsum[k] + gsum[128 + k];
; #pragma unroll
;         for (int i = 0; i < 16; ++i) {
;             const int s = 16 * sg + i; const float bt = bl[i] + off;
;             const float qr = bf2f(qr_[i]); const float q = qr * sigm(qr);
;             const float dA = fminf(fmaxf(bt - mref, -60.f), 60.f);
;             qA[s * 136 + k] = f2bf(q * __expf(dA)); qB[s * 136 + k] = f2bf(q * __expf(bt)); kh[s * 136 + k] = f2bf(kk[i] * __expf(-dA));
;         }
	v_mul_f32_e32 v31, 0x3fb8aa3b, v30
	v_exp_f32_e32 v28, v28
	v_exp_f32_e32 v31, v31
	v_cvt_pk_bf16_f32 v161, v161, v5
	ds_write_b16 v107, v161
	v_mul_f32_e32 v28, v29, v28
	v_mul_f32_e32 v31, v29, v31
	v_cvt_pk_bf16_f32 v28, v28, v5
	v_lshlrev_b32_e32 v29, 16, v81
	ds_write_b16 v107, v28 offset:18496
	v_mul_f32_e32 v28, 0xbfb8aa3b, v30
	v_mul_f32_e32 v30, 0xbfb8aa3b, v29
	v_exp_f32_e32 v30, v30
	v_exp_f32_e32 v28, v28
	v_cvt_pk_bf16_f32 v31, v31, v5
	ds_write_b16 v107, v31 offset:1088
	v_add_f32_e32 v30, 1.0, v30
	v_rcp_f32_e32 v30, v30
	v_mul_f32_e32 v28, v171, v28
	v_cvt_pk_bf16_f32 v28, v28, v5
	ds_write_b16 v107, v28 offset:35904
	v_add_f32_e32 v28, v35, v26
	v_mul_f32_e32 v29, v30, v29
	v_sub_f32_e32 v30, v28, v148
	v_med3_f32 v30, v30, s33, v243
	v_mul_f32_e32 v28, 0x3fb8aa3b, v28
	v_mul_f32_e32 v31, 0x3fb8aa3b, v30
	v_exp_f32_e32 v28, v28
	v_exp_f32_e32 v31, v31
	v_cvt_pk_bf16_f32 v160, v160, v5
	ds_write_b16 v107, v160 offset:272
	v_mul_f32_e32 v28, v29, v28
	v_mul_f32_e32 v31, v29, v31
	v_cvt_pk_bf16_f32 v28, v28, v5
	v_lshlrev_b32_e32 v29, 16, v79
	ds_write_b16 v107, v28 offset:18768
	v_mul_f32_e32 v28, 0xbfb8aa3b, v30
	v_mul_f32_e32 v30, 0xbfb8aa3b, v29
	v_exp_f32_e32 v30, v30
	v_exp_f32_e32 v28, v28
	v_cvt_pk_bf16_f32 v31, v31, v5
	ds_write_b16 v107, v31 offset:1360
	v_add_f32_e32 v30, 1.0, v30
	v_rcp_f32_e32 v30, v30
	v_mul_f32_e32 v28, v158, v28
	v_cvt_pk_bf16_f32 v28, v28, v5
	ds_write_b16 v107, v28 offset:36176
	v_add_f32_e32 v28, v32, v26
	v_mul_f32_e32 v29, v30, v29
	v_sub_f32_e32 v30, v28, v148
	v_med3_f32 v30, v30, s33, v243
	v_mul_f32_e32 v28, 0x3fb8aa3b, v28
	v_mul_f32_e32 v31, 0x3fb8aa3b, v30
	v_exp_f32_e32 v28, v28
	v_exp_f32_e32 v31, v31
	v_cvt_pk_bf16_f32 v159, v159, v5
	ds_write_b16 v107, v159 offset:544
	v_mul_f32_e32 v28, v29, v28
	v_mul_f32_e32 v31, v29, v31
	v_cvt_pk_bf16_f32 v28, v28, v5
	v_lshlrev_b32_e32 v29, 16, v78
	ds_write_b16 v107, v28 offset:19040
	v_mul_f32_e32 v28, 0xbfb8aa3b, v30
	v_mul_f32_e32 v30, 0xbfb8aa3b, v29
	v_exp_f32_e32 v30, v30
	v_exp_f32_e32 v28, v28
	v_cvt_pk_bf16_f32 v31, v31, v5
	ds_write_b16 v107, v31 offset:1632
	v_add_f32_e32 v30, 1.0, v30
	v_rcp_f32_e32 v30, v30
	v_mul_f32_e32 v28, v157, v28
	v_cvt_pk_bf16_f32 v28, v28, v5
	ds_write_b16 v107, v28 offset:36448
	v_add_f32_e32 v28, v37, v26
	v_mul_f32_e32 v29, v30, v29
	v_sub_f32_e32 v30, v28, v148
	v_med3_f32 v30, v30, s33, v243
	v_mul_f32_e32 v28, 0x3fb8aa3b, v28
	v_mul_f32_e32 v31, 0x3fb8aa3b, v30
	v_exp_f32_e32 v28, v28
	v_exp_f32_e32 v31, v31
	v_cvt_pk_bf16_f32 v33, v33, v5
	ds_write_b16 v107, v33 offset:816
	v_mul_f32_e32 v28, v29, v28
	v_mul_f32_e32 v31, v29, v31
	v_cvt_pk_bf16_f32 v28, v28, v5
	v_lshlrev_b32_e32 v29, 16, v90
	ds_write_b16 v107, v28 offset:19312
	v_mul_f32_e32 v28, 0xbfb8aa3b, v30
	v_mul_f32_e32 v30, 0xbfb8aa3b, v29
	v_exp_f32_e32 v30, v30
	v_exp_f32_e32 v28, v28
	v_cvt_pk_bf16_f32 v31, v31, v5
	ds_write_b16 v107, v31 offset:1904
	v_add_f32_e32 v30, 1.0, v30
	v_rcp_f32_e32 v30, v30
	v_mul_f32_e32 v28, v156, v28
	v_cvt_pk_bf16_f32 v28, v28, v5
	ds_write_b16 v107, v28 offset:36720
	v_add_f32_e32 v28, v34, v26
	v_mul_f32_e32 v29, v30, v29
	v_sub_f32_e32 v30, v28, v148
	v_med3_f32 v30, v30, s33, v243
	v_mul_f32_e32 v28, 0x3fb8aa3b, v28
	v_mul_f32_e32 v31, 0x3fb8aa3b, v30
	v_exp_f32_e32 v28, v28
	v_exp_f32_e32 v31, v31
	v_mul_f32_e32 v28, v29, v28
	v_mul_f32_e32 v31, v29, v31
	v_cvt_pk_bf16_f32 v28, v28, v5
	v_lshlrev_b32_e32 v29, 16, v89
	ds_write_b16 v107, v28 offset:19584
	v_mul_f32_e32 v28, 0xbfb8aa3b, v30
	v_mul_f32_e32 v30, 0xbfb8aa3b, v29
	v_exp_f32_e32 v30, v30
	v_exp_f32_e32 v28, v28
	v_cvt_pk_bf16_f32 v31, v31, v5
	ds_write_b16 v107, v31 offset:2176
	v_add_f32_e32 v30, 1.0, v30
	v_rcp_f32_e32 v30, v30
	v_mul_f32_e32 v28, v155, v28
	v_cvt_pk_bf16_f32 v28, v28, v5
	ds_write_b16 v107, v28 offset:36992
	v_add_f32_e32 v28, v39, v26
	v_mul_f32_e32 v29, v30, v29
	v_sub_f32_e32 v30, v28, v148
	v_med3_f32 v30, v30, s33, v243
	v_mul_f32_e32 v28, 0x3fb8aa3b, v28
	v_mul_f32_e32 v31, 0x3fb8aa3b, v30
	v_exp_f32_e32 v28, v28
	v_exp_f32_e32 v31, v31
	v_mul_f32_e32 v28, v29, v28
	v_mul_f32_e32 v31, v29, v31
	v_cvt_pk_bf16_f32 v28, v28, v5
	v_lshlrev_b32_e32 v29, 16, v87
	ds_write_b16 v107, v28 offset:19856
	v_mul_f32_e32 v28, 0xbfb8aa3b, v30
	v_mul_f32_e32 v30, 0xbfb8aa3b, v29
	v_exp_f32_e32 v30, v30
	v_exp_f32_e32 v28, v28
	v_cvt_pk_bf16_f32 v31, v31, v5
	ds_write_b16 v107, v31 offset:2448
	v_add_f32_e32 v30, 1.0, v30
	v_rcp_f32_e32 v30, v30
	v_mul_f32_e32 v28, v154, v28
	v_cvt_pk_bf16_f32 v28, v28, v5
	ds_write_b16 v107, v28 offset:37264
	v_add_f32_e32 v28, v36, v26
	v_mul_f32_e32 v29, v30, v29
	v_sub_f32_e32 v30, v28, v148
	v_med3_f32 v30, v30, s33, v243
	v_mul_f32_e32 v28, 0x3fb8aa3b, v28
	v_mul_f32_e32 v31, 0x3fb8aa3b, v30
	v_exp_f32_e32 v28, v28
	v_exp_f32_e32 v31, v31
	v_mul_f32_e32 v28, v29, v28
	v_mul_f32_e32 v31, v29, v31
	v_cvt_pk_bf16_f32 v28, v28, v5
	v_lshlrev_b32_e32 v29, 16, v86
	ds_write_b16 v107, v28 offset:20128
	v_mul_f32_e32 v28, 0xbfb8aa3b, v30
	v_mul_f32_e32 v30, 0xbfb8aa3b, v29
	v_exp_f32_e32 v30, v30
	v_exp_f32_e32 v28, v28
	v_cvt_pk_bf16_f32 v31, v31, v5
	ds_write_b16 v107, v31 offset:2720
	v_add_f32_e32 v30, 1.0, v30
	v_rcp_f32_e32 v30, v30
	v_mul_f32_e32 v28, v153, v28
	v_cvt_pk_bf16_f32 v28, v28, v5
	ds_write_b16 v107, v28 offset:37536
	v_add_f32_e32 v28, v41, v26
	v_mul_f32_e32 v29, v30, v29
	v_sub_f32_e32 v30, v28, v148
	v_med3_f32 v30, v30, s33, v243
	v_mul_f32_e32 v28, 0x3fb8aa3b, v28
	v_mul_f32_e32 v31, 0x3fb8aa3b, v30
	v_exp_f32_e32 v28, v28
	v_exp_f32_e32 v31, v31
	v_mul_f32_e32 v28, v29, v28
	v_mul_f32_e32 v31, v29, v31
	v_cvt_pk_bf16_f32 v28, v28, v5
	v_lshlrev_b32_e32 v29, 16, v101
; __device__ __forceinline__ float bf2f(bf16_t b) { return __uint_as_float(((unsigned)b) << 16); }
; __device__ __forceinline__ bf16_t f2bf(float f) { return (bf16_t)(cvt_pk_bf16(f, 0.f) & 0xffffu); }
; __device__ __forceinline__ float sigm(float x) { return rcpf_(1.f + __expf(-x)); }
; __device__ __forceinline__ void phase_hgrn_c3(const Params& p, int l, int bid, int nblk, LAS unsigned char* lds) {
;     ...
;         const float mref = gsum[k] + gsum[128 + k];
; #pragma unroll
;         for (int i = 0; i < 16; ++i) {
;             const int s = 16 * sg + i; const float bt = bl[i] + off;
;             const float qr = bf2f(qr_[i]); const float q = qr * sigm(qr);
;             const float dA = fminf(fmaxf(bt - mref, -60.f), 60.f);
;             qA[s * 136 + k] = f2bf(q * __expf(dA)); qB[s * 136 + k] = f2bf(q * __expf(bt)); kh[s * 136 + k] = f2bf(kk[i] * __expf(-dA));
;         }
;         if (job + nblk < NCHUNK * 8) C3_LOAD(job + nblk);
	ds_write_b16 v107, v28 offset:20400
	v_mul_f32_e32 v28, 0xbfb8aa3b, v30
	v_mul_f32_e32 v30, 0xbfb8aa3b, v29
	v_exp_f32_e32 v30, v30
	v_exp_f32_e32 v28, v28
	v_cvt_pk_bf16_f32 v31, v31, v5
	ds_write_b16 v107, v31 offset:2992
	v_add_f32_e32 v30, 1.0, v30
	v_rcp_f32_e32 v30, v30
	v_mul_f32_e32 v28, v152, v28
	v_cvt_pk_bf16_f32 v28, v28, v5
	ds_write_b16 v107, v28 offset:37808
	v_add_f32_e32 v28, v38, v26
	v_mul_f32_e32 v29, v30, v29
	v_sub_f32_e32 v30, v28, v148
	v_med3_f32 v30, v30, s33, v243
	v_mul_f32_e32 v28, 0x3fb8aa3b, v28
	v_mul_f32_e32 v31, 0x3fb8aa3b, v30
	v_exp_f32_e32 v28, v28
	v_exp_f32_e32 v31, v31
	v_mul_f32_e32 v28, v29, v28
	v_mul_f32_e32 v31, v29, v31
	v_cvt_pk_bf16_f32 v28, v28, v5
	v_lshlrev_b32_e32 v29, 16, v99
	ds_write_b16 v107, v28 offset:20672
	v_mul_f32_e32 v28, 0xbfb8aa3b, v30
	v_mul_f32_e32 v30, 0xbfb8aa3b, v29
	v_exp_f32_e32 v30, v30
	v_exp_f32_e32 v28, v28
	v_cvt_pk_bf16_f32 v31, v31, v5
	ds_write_b16 v107, v31 offset:3264
	v_add_f32_e32 v30, 1.0, v30
	v_rcp_f32_e32 v30, v30
	v_mul_f32_e32 v28, v151, v28
	v_cvt_pk_bf16_f32 v28, v28, v5
	ds_write_b16 v107, v28 offset:38080
	v_add_f32_e32 v28, v63, v26
	v_mul_f32_e32 v29, v30, v29
	v_sub_f32_e32 v30, v28, v148
	v_med3_f32 v30, v30, s33, v243
	v_mul_f32_e32 v28, 0x3fb8aa3b, v28
	v_mul_f32_e32 v31, 0x3fb8aa3b, v30
	v_exp_f32_e32 v28, v28
	v_exp_f32_e32 v31, v31
	v_mul_f32_e32 v28, v29, v28
	v_mul_f32_e32 v31, v29, v31
	v_cvt_pk_bf16_f32 v28, v28, v5
	v_lshlrev_b32_e32 v29, 16, v97
	ds_write_b16 v107, v28 offset:20944
	v_mul_f32_e32 v28, 0xbfb8aa3b, v30
	v_mul_f32_e32 v30, 0xbfb8aa3b, v29
	v_exp_f32_e32 v30, v30
	v_exp_f32_e32 v28, v28
	v_cvt_pk_bf16_f32 v31, v31, v5
	ds_write_b16 v107, v31 offset:3536
	v_add_f32_e32 v30, 1.0, v30
	v_rcp_f32_e32 v30, v30
	v_mul_f32_e32 v28, v150, v28
	v_cvt_pk_bf16_f32 v28, v28, v5
	ds_write_b16 v107, v28 offset:38352
	v_add_f32_e32 v28, v40, v26
	v_mul_f32_e32 v29, v30, v29
	v_sub_f32_e32 v30, v28, v148
	v_mul_f32_e32 v28, 0x3fb8aa3b, v28
	v_exp_f32_e32 v28, v28
	v_med3_f32 v30, v30, s33, v243
	v_mul_f32_e32 v31, 0x3fb8aa3b, v30
	v_exp_f32_e32 v31, v31
	v_mul_f32_e32 v28, v29, v28
	v_cvt_pk_bf16_f32 v28, v28, v5
	ds_write_b16 v107, v28 offset:21216
	v_mul_f32_e32 v28, 0xbfb8aa3b, v30
	v_exp_f32_e32 v28, v28
	v_mul_f32_e32 v31, v29, v31
	v_add_f32_e32 v26, v67, v26
	v_cvt_pk_bf16_f32 v31, v31, v5
	v_mul_f32_e32 v28, v149, v28
	v_cvt_pk_bf16_f32 v28, v28, v5
	ds_write_b16 v107, v28 offset:38624
	v_lshlrev_b32_e32 v28, 16, v96
	v_mul_f32_e32 v29, 0xbfb8aa3b, v28
	v_exp_f32_e32 v29, v29
	ds_write_b16 v107, v31 offset:3808
	v_add_f32_e32 v29, 1.0, v29
	v_rcp_f32_e32 v29, v29
	s_nop 0
	v_mul_f32_e32 v28, v29, v28
	v_sub_f32_e32 v29, v26, v148
	v_mul_f32_e32 v26, 0x3fb8aa3b, v26
	v_exp_f32_e32 v26, v26
	v_med3_f32 v29, v29, s33, v243
	v_mul_f32_e32 v30, 0x3fb8aa3b, v29
	v_exp_f32_e32 v30, v30
	v_mul_f32_e32 v26, v28, v26
	v_cvt_pk_bf16_f32 v26, v26, v5
	ds_write_b16 v107, v26 offset:21488
	v_mul_f32_e32 v26, 0xbfb8aa3b, v29
	v_exp_f32_e32 v26, v26
	v_mul_f32_e32 v30, v28, v30
	v_cvt_pk_bf16_f32 v30, v30, v5
	ds_write_b16 v107, v30 offset:4080
	v_mul_f32_e32 v26, v27, v26
	v_cvt_pk_bf16_f32 v26, v26, v5
	ds_write_b16 v107, v26 offset:38896
	s_cbranch_scc1 .LBB0_245
	s_add_i32 s38, s82, s83
	s_add_i32 s39, s84, s85
	s_andn2_b32 s38, s38, 63
	s_and_b32 s39, s39, 0x380
	s_ashr_i32 s47, s46, 31
	s_lshl_b64 s[88:89], s[46:47], 15
	s_load_dwordx2 s[80:81], s[0:1], 0x128
	s_add_u32 s98, s44, 0x2000
	s_addc_u32 s99, s45, 0
	v_or_b32_e32 v2, s39, v69
	v_add_u32_e32 v12, s38, v100
	v_mov_b64_e32 v[18:19], s[44:45]
	v_mov_b32_e32 v63, v5
	v_lshlrev_b32_e32 v2, 1, v2
	v_mul_lo_u32 v0, v12, s43
	v_add_u32_e32 v0, v0, v2
	v_add_u32_e32 v6, 0x5800, v0
	v_add_u32_e32 v8, 0xb000, v0
	v_add_u32_e32 v10, 0x10800, v0
	global_load_ushort v72, v0, s[98:99] offset:2048
	global_load_ushort v75, v6, s[98:99] offset:2048
	global_load_ushort v76, v8, s[98:99] offset:2048
	global_load_ushort v77, v10, s[98:99] offset:2048
	global_load_ushort v70, v10, s[98:99]
	global_load_ushort v71, v8, s[98:99]
	global_load_ushort v73, v6, s[98:99]
	global_load_ushort v74, v0, s[98:99]
	v_add_u32_e32 v0, 0x16000, v0
	v_add_u32_e32 v6, 0x16000, v6
	v_add_u32_e32 v8, 0x16000, v8
	v_add_u32_e32 v10, 0x16000, v10
	global_load_ushort v80, v0, s[98:99] offset:2048
	global_load_ushort v83, v6, s[98:99] offset:2048
	global_load_ushort v84, v8, s[98:99] offset:2048
	global_load_ushort v85, v10, s[98:99] offset:2048
	global_load_ushort v78, v10, s[98:99]
	global_load_ushort v79, v8, s[98:99]
	global_load_ushort v81, v6, s[98:99]
	global_load_ushort v82, v0, s[98:99]
	v_add_u32_e32 v0, 0x16000, v0
	v_add_u32_e32 v6, 0x16000, v6
	v_add_u32_e32 v8, 0x16000, v8
	v_add_u32_e32 v10, 0x16000, v10
	global_load_ushort v88, v0, s[98:99] offset:2048
	global_load_ushort v91, v6, s[98:99] offset:2048
	global_load_ushort v92, v8, s[98:99] offset:2048
	global_load_ushort v93, v10, s[98:99] offset:2048
	global_load_ushort v86, v10, s[98:99]
	global_load_ushort v87, v8, s[98:99]
	global_load_ushort v89, v6, s[98:99]
	global_load_ushort v90, v0, s[98:99]
	v_add_u32_e32 v0, 0x16000, v0
	v_add_u32_e32 v6, 0x16000, v6
	v_add_u32_e32 v8, 0x16000, v8
	v_add_u32_e32 v10, 0x16000, v10
	global_load_ushort v102, v0, s[98:99] offset:2048
	global_load_ushort v103, v6, s[98:99] offset:2048
	global_load_ushort v104, v8, s[98:99] offset:2048
	global_load_ushort v105, v10, s[98:99] offset:2048
	global_load_ushort v96, v10, s[98:99]
	global_load_ushort v97, v8, s[98:99]
	global_load_ushort v99, v6, s[98:99]
	global_load_ushort v101, v0, s[98:99]
	s_waitcnt lgkmcnt(0)
	s_add_u32 s80, s80, s88
	s_addc_u32 s81, s81, s89
	v_or_b32_e32 v20, s38, v68
	v_lshl_add_u64 v[10:11], s[80:81], 0, v[62:63]
	v_mad_i64_i32 v[18:19], s[80:81], v20, s43, v[18:19]
	s_lshl_b32 s38, s39, 1
	s_mov_b32 s39, s51
	v_lshl_add_u64 v[18:19], v[18:19], 0, s[38:39]
	v_lshl_add_u64 v[18:19], v[18:19], 0, s[62:63]
	v_lshl_add_u64 v[0:1], v[42:43], 1, v[10:11]
	v_lshl_add_u64 v[6:7], v[50:51], 1, v[10:11]
	v_lshl_add_u64 v[12:13], v[52:53], 1, v[10:11]
	v_lshl_add_u64 v[14:15], v[54:55], 1, v[10:11]
	v_lshl_add_u64 v[20:21], v[44:45], 1, v[18:19]
	v_lshl_add_u64 v[22:23], v[48:49], 1, v[18:19]
	global_load_dwordx4 v[0:3], v[0:1], off
	s_nop 0
	global_load_dwordx4 v[6:9], v[6:7], off
	s_nop 0
	global_load_dwordx4 v[10:13], v[12:13], off
	s_nop 0
	global_load_dwordx4 v[14:17], v[14:15], off
	s_nop 0
	global_load_dwordx4 v[18:21], v[20:21], off
	s_nop 0
	global_load_dwordx4 v[22:25], v[22:23], off

; __device__ __forceinline__ float rcpf_(float x) { return __builtin_amdgcn_rcpf(x); }
; __device__ __forceinline__ u32x4 pack8(const float* e) { u32x4 w; w.x = cvt_pk_bf16(e[0], e[1]); w.y = cvt_pk_bf16(e[2], e[3]); w.z = cvt_pk_bf16(e[4], e[5]); w.w = cvt_pk_bf16(e[6], e[7]); return w; }
; __device__ __forceinline__ void unpack8(u32x4 w, float* e) { e[0] = lo_bf(w.x); e[1] = hi_bf(w.x); e[2] = lo_bf(w.y); e[3] = hi_bf(w.y); e[4] = lo_bf(w.z); e[5] = hi_bf(w.z); e[6] = lo_bf(w.w); e[7] = hi_bf(w.w); }
; __device__ __forceinline__ void phase_ffn_conv(const Params& p, int l, int bid, int nblk) {
;     ...
;                 u32x4 ur[6], vr[4];
; #pragma unroll
;                 for (int j = 0; j < 6; ++j) { const int i = i0 - 2 + j; ur[j] = (i >= 0 || !seq0) ? *(const u32x4*)(p.UV + (size_t)(rb * 64 + i) * 6144 + c8) : (u32x4){0u, 0u, 0u, 0u}; }
; #pragma unroll
;                 for (int j = 0; j < 4; ++j) vr[j] = *(const u32x4*)(p.UV + (size_t)(rbase + j) * 6144 + 3072 + c8);
; #pragma unroll
;                 for (int u = 0; u < 4; ++u) { const int r = rbase + u; const int i = i0 + u;
;                     float u0[8], u1[8], u2[8], vv[8], o[8];
;                     unpack8(ur[u + 2], u0); unpack8(ur[u + 1], u1); unpack8(ur[u], u2); unpack8(vr[u], vv);
;                     if (r >= SEQ && i < 2) {
;                         const float* cache = p.cache_conv_ffn + (size_t)((l * 8 + ((r - SEQ) >> 6)) * 2) * 3072 + c8;
; #pragma unroll
;                         for (int j = 0; j < 8; ++j) { if (i == 0) { u1[j] = cache[3072 + j]; u2[j] = cache[j]; } else { u2[j] = cache[3072 + j]; } }
;                     }
; #pragma unroll
;                     for (int j = 0; j < 8; ++j) {
;                         const float uc = bb[j] + w2[j] * u0[j] + w1[j] * u1[j] + w0[j] * u2[j];
;                         const float y = 0.7978845608028654f * (uc + 0.044715f * uc * uc * uc);
;                         const float th = 1.f - 2.f * rcpf_(1.f + __expf(2.f * y));
;                         o[j] = 0.5f * uc * (1.f + th) * vv[j];
;                     }
;                     *(u32x4*)(p.Gf + (size_t)r * 3072 + c8) = pack8(o);
.LBB0_697:
	s_or_b64 exec, exec, s[20:21]
	v_mov_b64_e32 v[122:123], s[16:17]
	v_mad_i64_i32 v[142:143], s[98:99], v82, s95, v[122:123]
	v_lshlrev_b32_e32 v140, 1, v66
	v_mov_b32_e32 v141, 0
	v_lshl_add_u64 v[142:143], v[142:143], 0, v[140:141]
	s_mov_b64 s[98:99], 0x1800
	v_lshl_add_u64 v[142:143], v[142:143], 0, s[98:99]
	global_load_dwordx4 v[124:127], v[142:143], off
	s_mov_b64 s[98:99], 0x3000
	v_lshl_add_u64 v[142:143], v[142:143], 0, s[98:99]
	global_load_dwordx4 v[128:131], v[142:143], off
	v_lshl_add_u64 v[142:143], v[142:143], 0, s[98:99]
	global_load_dwordx4 v[132:135], v[142:143], off
	v_lshl_add_u64 v[142:143], v[142:143], 0, s[98:99]
	global_load_dwordx4 v[136:139], v[142:143], off
	v_mov_b64_e32 v[36:37], s[16:17]
	v_mad_i64_i32 v[50:51], s[20:21], v82, s95, v[36:37]
	v_lshlrev_b32_e32 v4, 1, v66
	v_lshl_add_u64 v[50:51], v[50:51], 0, v[4:5]
	v_add_co_u32_e32 v50, vcc, 0x1000, v50
	s_waitcnt vmcnt(4)
	v_lshlrev_b32_e32 v95, 16, v58
	v_addc_co_u32_e32 v51, vcc, 0, v51, vcc
	s_waitcnt vmcnt(3)
	v_mov_b32_e32 v96, v124
	v_mov_b32_e32 v97, v125
	v_mov_b32_e32 v98, v126
	v_mov_b32_e32 v99, v127
	v_lshlrev_b32_e32 v91, 16, v59
	v_and_b32_e32 v89, 0xffff0000, v59
	v_lshlrev_b32_e32 v87, 16, v60
	v_and_b32_e32 v85, 0xffff0000, v60
	v_lshlrev_b32_e32 v83, 16, v61
	v_and_b32_e32 v59, 0xffff0000, v61
	v_lshlrev_b32_e32 v61, 16, v42
	v_lshlrev_b32_e32 v60, 16, v46
	v_and_b32_e32 v93, 0xffff0000, v58
	v_add_u32_e32 v108, 1, v82
	v_mad_i64_i32 v[50:51], s[20:21], v108, s95, v[36:37]
	v_lshl_add_u64 v[50:51], v[50:51], 0, v[4:5]
	v_add_u32_e32 v106, 2, v82
	v_add_co_u32_e32 v50, vcc, 0x1000, v50
	v_mad_i64_i32 v[36:37], s[20:21], v106, s95, v[36:37]
	s_nop 0
	v_addc_co_u32_e32 v51, vcc, 0, v51, vcc
	v_lshl_add_u64 v[36:37], v[36:37], 0, v[4:5]
	v_add_co_u32_e32 v36, vcc, 0x1000, v36
	s_waitcnt vmcnt(2)
	v_mov_b32_e32 v54, v128
	v_mov_b32_e32 v55, v129
	v_mov_b32_e32 v56, v130
	v_mov_b32_e32 v57, v131
	s_nop 0
	v_addc_co_u32_e32 v37, vcc, 0, v37, vcc
	s_waitcnt vmcnt(1)
	v_mov_b32_e32 v50, v132
	v_mov_b32_e32 v51, v133
	v_mov_b32_e32 v52, v134
	v_mov_b32_e32 v53, v135
	v_and_b32_e32 v115, 0xffff0000, v44
	v_and_b32_e32 v114, 0xffff0000, v48
	v_lshlrev_b32_e32 v116, 16, v49
	v_lshlrev_b32_e32 v117, 16, v45
	v_and_b32_e32 v119, 0xffff0000, v45
	v_and_b32_e32 v118, 0xffff0000, v49
	s_load_dwordx2 s[20:21], s[0:1], 0x178
	v_lshl_add_u64 v[34:35], s[16:17], 0, v[34:35]
	v_lshl_add_u64 v[34:35], v[34:35], 0, v[4:5]
	v_add_co_u32_e32 v34, vcc, 0x1000, v34
	s_waitcnt vmcnt(2)
	v_lshlrev_b32_e32 v88, 16, v96
	v_and_b32_e32 v90, 0xffff0000, v96
	v_lshlrev_b32_e32 v92, 16, v97
	v_and_b32_e32 v94, 0xffff0000, v97
	v_lshlrev_b32_e32 v107, 16, v98
	v_and_b32_e32 v86, 0xffff0000, v98
	v_fma_f32 v98, v0, v95, v10
	v_pk_mul_f32 v[96:97], v[76:77], v[60:61]
	v_lshlrev_b32_e32 v84, 16, v99
	v_add_f32_e32 v60, v97, v98
	v_add_f32_e32 v60, v96, v60
	v_mul_f32_e32 v96, 0x3d372713, v60
	v_mul_f32_e32 v96, v60, v96
	v_fma_f32 v96, v60, v96, v60
	v_mul_f32_e32 v96, 0x3f4c422a, v96
	v_add_f32_e32 v96, v96, v96
	v_mul_f32_e32 v96, 0x3fb8aa3b, v96
	v_exp_f32_e32 v96, v96
	v_mul_f32_e32 v60, 0.5, v60
	v_and_b32_e32 v97, 0xffff0000, v42
	v_and_b32_e32 v58, 0xffff0000, v99
	v_add_f32_e32 v96, 1.0, v96
	v_rcp_f32_e32 v96, v96
	v_addc_co_u32_e32 v35, vcc, 0, v35, vcc
	s_waitcnt vmcnt(0)
	v_mov_b32_e32 v34, v136
	v_mov_b32_e32 v35, v137
	v_mov_b32_e32 v36, v138
	v_mov_b32_e32 v37, v139
	v_fma_f32 v96, v96, -2.0, 1.0
	v_add_f32_e32 v96, 1.0, v96
	v_mul_f32_e32 v60, v60, v96
	v_and_b32_e32 v96, 0xffff0000, v46
	v_mul_f32_e32 v60, v60, v88
	v_fma_f32 v88, v1, v93, v11
	v_pk_mul_f32 v[98:99], v[18:19], v[96:97]
	s_waitcnt vmcnt(2)
	v_lshlrev_b32_e32 v109, 16, v57
	v_add_f32_e32 v42, v99, v88
	v_add_f32_e32 v42, v98, v42
	v_mul_f32_e32 v46, 0x3d372713, v42
	v_mul_f32_e32 v46, v42, v46
	v_fma_f32 v46, v42, v46, v42
	v_mul_f32_e32 v46, 0x3f4c422a, v46
	v_add_f32_e32 v46, v46, v46
	v_mul_f32_e32 v46, 0x3fb8aa3b, v46
	v_exp_f32_e32 v46, v46
	v_mul_f32_e32 v42, 0.5, v42
	v_lshlrev_b32_e32 v98, 16, v47
	v_lshlrev_b32_e32 v99, 16, v43
	v_add_f32_e32 v46, 1.0, v46
	v_rcp_f32_e32 v46, v46
	v_pk_mul_f32 v[100:101], v[74:75], v[98:99]
	v_and_b32_e32 v43, 0xffff0000, v43
	v_fma_f32 v46, v46, -2.0, 1.0
	v_add_f32_e32 v46, 1.0, v46
	v_mul_f32_e32 v42, v42, v46
	v_mul_f32_e32 v88, v42, v90
	v_fma_f32 v42, v2, v91, v12
	v_add_f32_e32 v42, v101, v42
	v_add_f32_e32 v42, v100, v42
	v_mul_f32_e32 v46, 0x3d372713, v42
	v_mul_f32_e32 v46, v42, v46
	v_fma_f32 v46, v42, v46, v42
	v_mul_f32_e32 v46, 0x3f4c422a, v46
	v_add_f32_e32 v46, v46, v46
	v_mul_f32_e32 v46, 0x3fb8aa3b, v46
	v_exp_f32_e32 v46, v46
	v_mul_f32_e32 v42, 0.5, v42
	v_cvt_pk_bf16_f32 v110, v60, v88
	v_mov_b32_e32 v88, v43
	v_add_f32_e32 v46, 1.0, v46
	v_rcp_f32_e32 v46, v46
	s_nop 0
	v_fma_f32 v46, v46, -2.0, 1.0
	v_add_f32_e32 v46, 1.0, v46
	v_mul_f32_e32 v42, v42, v46
	v_mul_f32_e32 v90, v42, v92
	v_and_b32_e32 v42, 0xffff0000, v47
	v_fma_f32 v92, v3, v89, v13
	v_pk_mul_f32 v[46:47], v[20:21], v[42:43]
	s_nop 0
	v_add_f32_e32 v42, v47, v92
	v_add_f32_e32 v42, v46, v42
	v_mul_f32_e32 v46, 0x3d372713, v42
	v_mul_f32_e32 v46, v42, v46
	v_fma_f32 v46, v42, v46, v42
	v_mul_f32_e32 v46, 0x3f4c422a, v46
	v_add_f32_e32 v46, v46, v46
	v_mul_f32_e32 v46, 0x3fb8aa3b, v46
	v_exp_f32_e32 v46, v46
	v_mul_f32_e32 v42, 0.5, v42
	v_lshlrev_b32_e32 v47, 16, v44
	v_fma_f32 v92, v6, v87, v14
	v_add_f32_e32 v46, 1.0, v46
	v_rcp_f32_e32 v46, v46
	s_nop 0
	v_fma_f32 v46, v46, -2.0, 1.0
	v_add_f32_e32 v46, 1.0, v46
	v_mul_f32_e32 v42, v42, v46
	v_lshlrev_b32_e32 v46, 16, v48
	v_pk_mul_f32 v[100:101], v[72:73], v[46:47]
	v_mul_f32_e32 v42, v42, v94
	v_add_f32_e32 v46, v101, v92
	v_add_f32_e32 v46, v100, v46
	v_mul_f32_e32 v92, 0x3d372713, v46
	v_mul_f32_e32 v92, v46, v92
	v_fma_f32 v92, v46, v92, v46
	v_mul_f32_e32 v92, 0x3f4c422a, v92
	v_add_f32_e32 v92, v92, v92
	v_mul_f32_e32 v92, 0x3fb8aa3b, v92
	v_exp_f32_e32 v92, v92
	v_mul_f32_e32 v46, 0.5, v46
	v_pk_mul_f32 v[100:101], v[22:23], v[114:115]
	v_cvt_pk_bf16_f32 v111, v90, v42
	v_add_f32_e32 v92, 1.0, v92
	v_rcp_f32_e32 v92, v92
	v_mov_b32_e32 v94, v61
	v_mov_b32_e32 v90, v99
	v_pk_mul_f32 v[98:99], v[20:21], v[88:89]
	v_fma_f32 v92, v92, -2.0, 1.0
	v_add_f32_e32 v92, 1.0, v92
	v_mul_f32_e32 v46, v46, v92
	v_fma_f32 v92, v7, v85, v15
	v_add_f32_e32 v44, v101, v92
	v_add_f32_e32 v44, v100, v44
	v_mul_f32_e32 v48, 0x3d372713, v44
	v_mul_f32_e32 v48, v44, v48
	v_fma_f32 v48, v44, v48, v44
	v_mul_f32_e32 v48, 0x3f4c422a, v48
	v_add_f32_e32 v48, v48, v48
	v_mul_f32_e32 v48, 0x3fb8aa3b, v48
	v_exp_f32_e32 v48, v48
	v_mul_f32_e32 v44, 0.5, v44
	v_pk_mul_f32 v[100:101], v[70:71], v[116:117]
	v_mul_f32_e32 v46, v46, v107
	v_add_f32_e32 v48, 1.0, v48
	v_rcp_f32_e32 v48, v48
	v_and_b32_e32 v107, 0xffff0000, v57
	s_waitcnt vmcnt(1)
; __device__ __forceinline__ float rcpf_(float x) { return __builtin_amdgcn_rcpf(x); }
; __device__ __forceinline__ u32x4 pack8(const float* e) { u32x4 w; w.x = cvt_pk_bf16(e[0], e[1]); w.y = cvt_pk_bf16(e[2], e[3]); w.z = cvt_pk_bf16(e[4], e[5]); w.w = cvt_pk_bf16(e[6], e[7]); return w; }
; __device__ __forceinline__ void unpack8(u32x4 w, float* e) { e[0] = lo_bf(w.x); e[1] = hi_bf(w.x); e[2] = lo_bf(w.y); e[3] = hi_bf(w.y); e[4] = lo_bf(w.z); e[5] = hi_bf(w.z); e[6] = lo_bf(w.w); e[7] = hi_bf(w.w); }
; __device__ __forceinline__ void phase_ffn_conv(const Params& p, int l, int bid, int nblk) {
;     ...
;                 for (int u = 0; u < 4; ++u) { const int r = rbase + u; const int i = i0 + u;
;                     float u0[8], u1[8], u2[8], vv[8], o[8];
;                     unpack8(ur[u + 2], u0); unpack8(ur[u + 1], u1); unpack8(ur[u], u2); unpack8(vr[u], vv);
;                     if (r >= SEQ && i < 2) {
;                         const float* cache = p.cache_conv_ffn + (size_t)((l * 8 + ((r - SEQ) >> 6)) * 2) * 3072 + c8;
; #pragma unroll
;                         for (int j = 0; j < 8; ++j) { if (i == 0) { u1[j] = cache[3072 + j]; u2[j] = cache[j]; } else { u2[j] = cache[3072 + j]; } }
;                     }
; #pragma unroll
;                     for (int j = 0; j < 8; ++j) {
;                         const float uc = bb[j] + w2[j] * u0[j] + w1[j] * u1[j] + w0[j] * u2[j];
;                         const float y = 0.7978845608028654f * (uc + 0.044715f * uc * uc * uc);
;                         const float th = 1.f - 2.f * rcpf_(1.f + __expf(2.f * y));
;                         o[j] = 0.5f * uc * (1.f + th) * vv[j];
;                     }
;                     *(u32x4*)(p.Gf + (size_t)r * 3072 + c8) = pack8(o);
	v_and_b32_e32 v88, 0xffff0000, v50
	v_mov_b32_e32 v92, v97
	v_fma_f32 v48, v48, -2.0, 1.0
	v_add_f32_e32 v48, 1.0, v48
	v_mul_f32_e32 v44, v44, v48
	v_mul_f32_e32 v48, v44, v86
	v_fma_f32 v44, v8, v83, v16
	v_add_f32_e32 v44, v101, v44
	v_add_f32_e32 v44, v100, v44
	v_mul_f32_e32 v86, 0x3d372713, v44
	v_mul_f32_e32 v86, v44, v86
	v_fma_f32 v86, v44, v86, v44
	v_mul_f32_e32 v86, 0x3f4c422a, v86
	v_add_f32_e32 v86, v86, v86
	v_mul_f32_e32 v86, 0x3fb8aa3b, v86
	v_exp_f32_e32 v86, v86
	v_mul_f32_e32 v44, 0.5, v44
	v_cvt_pk_bf16_f32 v112, v46, v48
	v_lshlrev_b32_e32 v46, 16, v54
	v_add_f32_e32 v86, 1.0, v86
	v_rcp_f32_e32 v86, v86
	v_pk_mul_f32 v[120:121], v[18:19], v[92:93]
	v_lshlrev_b32_e32 v92, 16, v51
	v_and_b32_e32 v114, 0xffff0000, v54
	v_fma_f32 v86, v86, -2.0, 1.0
	v_add_f32_e32 v86, 1.0, v86
	v_mul_f32_e32 v44, v44, v86
	v_mul_f32_e32 v84, v44, v84
	v_fma_f32 v86, v9, v59, v17
	v_pk_mul_f32 v[44:45], v[24:25], v[118:119]
	v_pk_mul_f32 v[100:101], v[74:75], v[90:91]
	v_add_f32_e32 v45, v45, v86
	v_add_f32_e32 v44, v44, v45
	v_mul_f32_e32 v45, 0x3d372713, v44
	v_mul_f32_e32 v45, v44, v45
	v_fma_f32 v45, v44, v45, v44
	v_mul_f32_e32 v45, 0x3f4c422a, v45
	v_add_f32_e32 v45, v45, v45
	v_mul_f32_e32 v45, 0x3fb8aa3b, v45
	v_exp_f32_e32 v45, v45
	v_mul_f32_e32 v44, 0.5, v44
	v_mov_b32_e32 v86, v47
	v_pk_mul_f32 v[96:97], v[72:73], v[86:87]
	v_add_f32_e32 v45, 1.0, v45
	v_rcp_f32_e32 v45, v45
	v_lshlrev_b32_e32 v86, 16, v52
	v_and_b32_e32 v90, 0xffff0000, v52
	v_lshlrev_b32_e32 v116, 16, v55
	v_fma_f32 v45, v45, -2.0, 1.0
	v_add_f32_e32 v45, 1.0, v45
	v_mul_f32_e32 v44, v44, v45
	v_mul_f32_e32 v44, v44, v58
	v_cvt_pk_bf16_f32 v113, v84, v44
	s_waitcnt lgkmcnt(0)
	v_mov_b64_e32 v[44:45], s[20:21]
	v_mad_i64_i32 v[48:49], s[22:23], v82, s40, v[44:45]
	v_lshl_add_u64 v[48:49], v[48:49], 0, v[4:5]
	v_mad_i64_i32 v[42:43], s[22:23], v108, s40, v[44:45]
	global_store_dwordx4 v[48:49], v[110:113], off
	v_lshl_add_u64 v[48:49], v[42:43], 0, v[4:5]
	v_lshlrev_b32_e32 v42, 16, v30
	v_pk_mul_f32 v[112:113], v[76:77], v[94:95]
	v_fma_f32 v47, v0, v42, v10
	v_add_f32_e32 v47, v113, v47
	v_mov_b32_e32 v82, v117
	v_add_f32_e32 v47, v112, v47
	v_lshlrev_b32_e32 v111, 16, v56
	v_and_b32_e32 v110, 0xffff0000, v56
	v_pk_mul_f32 v[56:57], v[70:71], v[82:83]
	v_lshlrev_b32_e32 v82, 16, v50
	v_mul_f32_e32 v50, 0x3d372713, v47
	v_mul_f32_e32 v50, v47, v50
	v_fma_f32 v50, v47, v50, v47
	v_mul_f32_e32 v50, 0x3f4c422a, v50
	v_add_f32_e32 v50, v50, v50
	v_mul_f32_e32 v50, 0x3fb8aa3b, v50
	v_exp_f32_e32 v50, v50
	v_mul_f32_e32 v47, 0.5, v47
	v_lshlrev_b32_e32 v43, 16, v38
	v_and_b32_e32 v94, 0xffff0000, v51
	v_add_f32_e32 v50, 1.0, v50
	v_rcp_f32_e32 v50, v50
	v_fma_f32 v51, v0, v43, v10
	v_mov_b32_e32 v84, v115
	v_mov_b32_e32 v58, v119
	v_fma_f32 v50, v50, -2.0, 1.0
	v_add_f32_e32 v50, 1.0, v50
	v_mul_f32_e32 v47, v47, v50
	v_mul_f32_e32 v50, v47, v46
	v_mov_b32_e32 v46, v95
	v_mov_b32_e32 v47, v42
	v_pk_mul_f32 v[46:47], v[76:77], v[46:47]
	v_and_b32_e32 v118, 0xffff0000, v55
	v_add_f32_e32 v47, v47, v51
	v_add_f32_e32 v46, v46, v47
	v_mul_f32_e32 v47, 0x3d372713, v46
	v_mul_f32_e32 v47, v46, v47
	v_fma_f32 v47, v46, v47, v46
	v_mul_f32_e32 v47, 0x3f4c422a, v47
	v_add_f32_e32 v47, v47, v47
	v_mul_f32_e32 v47, 0x3fb8aa3b, v47
	v_exp_f32_e32 v47, v47
	v_mul_f32_e32 v46, 0.5, v46
	v_pk_mul_f32 v[60:61], v[22:23], v[84:85]
	v_pk_mul_f32 v[54:55], v[24:25], v[58:59]
	v_add_f32_e32 v47, 1.0, v47
	v_rcp_f32_e32 v47, v47
	v_lshlrev_b32_e32 v84, 16, v53
	v_and_b32_e32 v58, 0xffff0000, v53
	v_mad_i64_i32 v[44:45], s[22:23], v106, s40, v[44:45]
	v_fma_f32 v47, v47, -2.0, 1.0
	v_add_f32_e32 v47, 1.0, v47
	v_mul_f32_e32 v46, v46, v47
	v_mul_f32_e32 v82, v46, v82
	v_and_b32_e32 v46, 0xffff0000, v30
	v_fma_f32 v30, v1, v46, v11
	v_add_f32_e32 v30, v121, v30
	v_add_f32_e32 v30, v120, v30
	v_and_b32_e32 v47, 0xffff0000, v38
	v_mul_f32_e32 v38, 0x3d372713, v30
	v_mul_f32_e32 v38, v30, v38
	v_fma_f32 v38, v30, v38, v30
	v_mul_f32_e32 v38, 0x3f4c422a, v38
	v_add_f32_e32 v38, v38, v38
	v_mul_f32_e32 v38, 0x3fb8aa3b, v38
	v_exp_f32_e32 v38, v38
	v_mul_f32_e32 v30, 0.5, v30
	v_mov_b32_e32 v51, v46
	v_lshl_add_u64 v[44:45], v[44:45], 0, v[4:5]
	v_add_f32_e32 v38, 1.0, v38
	v_rcp_f32_e32 v38, v38
	s_nop 0
	v_fma_f32 v38, v38, -2.0, 1.0
	v_add_f32_e32 v38, 1.0, v38
	v_mul_f32_e32 v30, v30, v38
	v_mul_f32_e32 v30, v30, v114
	v_cvt_pk_bf16_f32 v30, v50, v30
	v_mov_b32_e32 v50, v93
	v_fma_f32 v38, v1, v47, v11
	v_pk_mul_f32 v[50:51], v[18:19], v[50:51]
	s_nop 0
	v_add_f32_e32 v38, v51, v38
	v_add_f32_e32 v38, v50, v38
	v_mul_f32_e32 v50, 0x3d372713, v38
	v_mul_f32_e32 v50, v38, v50
	v_fma_f32 v50, v38, v50, v38
	v_mul_f32_e32 v50, 0x3f4c422a, v50
	v_add_f32_e32 v50, v50, v50
	v_mul_f32_e32 v50, 0x3fb8aa3b, v50
	v_exp_f32_e32 v50, v50
	v_mul_f32_e32 v38, 0.5, v38
	v_lshlrev_b32_e32 v51, 16, v39
	v_and_b32_e32 v39, 0xffff0000, v39
	v_add_f32_e32 v50, 1.0, v50
	v_rcp_f32_e32 v50, v50
	s_nop 0
	v_fma_f32 v50, v50, -2.0, 1.0
	v_add_f32_e32 v50, 1.0, v50
	v_mul_f32_e32 v38, v38, v50
	v_lshlrev_b32_e32 v50, 16, v31
	v_mul_f32_e32 v88, v38, v88
	v_fma_f32 v38, v2, v50, v12
	v_add_f32_e32 v38, v101, v38
	v_add_f32_e32 v38, v100, v38
	v_mul_f32_e32 v52, 0x3d372713, v38
	v_mul_f32_e32 v52, v38, v52
	v_fma_f32 v52, v38, v52, v38
	v_mul_f32_e32 v52, 0x3f4c422a, v52
	v_add_f32_e32 v52, v52, v52
	v_mul_f32_e32 v52, 0x3fb8aa3b, v52
	v_exp_f32_e32 v52, v52
	v_mul_f32_e32 v38, 0.5, v38
	v_mov_b32_e32 v53, v50
	v_add_f32_e32 v52, 1.0, v52
	v_rcp_f32_e32 v52, v52
	s_nop 0
	v_fma_f32 v52, v52, -2.0, 1.0
	v_add_f32_e32 v52, 1.0, v52
	v_mul_f32_e32 v38, v38, v52
	v_mov_b32_e32 v52, v91
	v_mul_f32_e32 v93, v38, v116
; __device__ __forceinline__ float rcpf_(float x) { return __builtin_amdgcn_rcpf(x); }
; __device__ __forceinline__ u32x4 pack8(const float* e) { u32x4 w; w.x = cvt_pk_bf16(e[0], e[1]); w.y = cvt_pk_bf16(e[2], e[3]); w.z = cvt_pk_bf16(e[4], e[5]); w.w = cvt_pk_bf16(e[6], e[7]); return w; }
; __device__ __forceinline__ void unpack8(u32x4 w, float* e) { e[0] = lo_bf(w.x); e[1] = hi_bf(w.x); e[2] = lo_bf(w.y); e[3] = hi_bf(w.y); e[4] = lo_bf(w.z); e[5] = hi_bf(w.z); e[6] = lo_bf(w.w); e[7] = hi_bf(w.w); }
; __device__ __forceinline__ void phase_ffn_conv(const Params& p, int l, int bid, int nblk) {
;     ...
;                 for (int u = 0; u < 4; ++u) { const int r = rbase + u; const int i = i0 + u;
;                     float u0[8], u1[8], u2[8], vv[8], o[8];
;                     unpack8(ur[u + 2], u0); unpack8(ur[u + 1], u1); unpack8(ur[u], u2); unpack8(vr[u], vv);
;                     if (r >= SEQ && i < 2) {
;                         const float* cache = p.cache_conv_ffn + (size_t)((l * 8 + ((r - SEQ) >> 6)) * 2) * 3072 + c8;
; #pragma unroll
;                         for (int j = 0; j < 8; ++j) { if (i == 0) { u1[j] = cache[3072 + j]; u2[j] = cache[j]; } else { u2[j] = cache[3072 + j]; } }
;                     }
; #pragma unroll
;                     for (int j = 0; j < 8; ++j) {
;                         const float uc = bb[j] + w2[j] * u0[j] + w1[j] * u1[j] + w0[j] * u2[j];
;                         const float y = 0.7978845608028654f * (uc + 0.044715f * uc * uc * uc);
;                         const float th = 1.f - 2.f * rcpf_(1.f + __expf(2.f * y));
;                         o[j] = 0.5f * uc * (1.f + th) * vv[j];
;                     }
;                     *(u32x4*)(p.Gf + (size_t)r * 3072 + c8) = pack8(o);
;                     if (i >= 62 && (rb == 255 || r >= SEQ)) {
;                         float* dst = r < SEQ ? p.out + O_FP + (size_t)(l * 2 + (i - 62)) * 3072 + c8 : p.out + O_FS + (size_t)((l * 8 + ((r - SEQ) >> 6)) * 2 + (i - 62)) * 3072 + c8;
; #pragma unroll
;                         for (int j = 0; j < 8; ++j) dst[j] = u0[j];
;                     }
	v_fma_f32 v38, v2, v51, v12
	v_pk_mul_f32 v[52:53], v[74:75], v[52:53]
	s_nop 0
	v_add_f32_e32 v38, v53, v38
	v_add_f32_e32 v38, v52, v38
	v_mul_f32_e32 v52, 0x3d372713, v38
	v_mul_f32_e32 v52, v38, v52
	v_fma_f32 v52, v38, v52, v38
	v_mul_f32_e32 v52, 0x3f4c422a, v52
	v_add_f32_e32 v52, v52, v52
	v_mul_f32_e32 v52, 0x3fb8aa3b, v52
	v_exp_f32_e32 v52, v52
	v_mul_f32_e32 v38, 0.5, v38
	v_add_f32_e32 v52, 1.0, v52
	v_rcp_f32_e32 v52, v52
	s_nop 0
	v_fma_f32 v52, v52, -2.0, 1.0
	v_add_f32_e32 v52, 1.0, v52
	v_mul_f32_e32 v38, v38, v52
	v_mul_f32_e32 v91, v38, v92
	v_and_b32_e32 v38, 0xffff0000, v31
	v_fma_f32 v31, v3, v38, v13
	v_add_f32_e32 v31, v99, v31
	v_add_f32_e32 v31, v98, v31
	v_mul_f32_e32 v52, 0x3d372713, v31
	v_mul_f32_e32 v52, v31, v52
	v_fma_f32 v52, v31, v52, v31
	v_mul_f32_e32 v52, 0x3f4c422a, v52
	v_add_f32_e32 v52, v52, v52
	v_mul_f32_e32 v52, 0x3fb8aa3b, v52
	v_exp_f32_e32 v52, v52
	v_mul_f32_e32 v31, 0.5, v31
	v_mov_b32_e32 v53, v38
	v_fma_f32 v92, v3, v39, v13
	v_add_f32_e32 v52, 1.0, v52
	v_rcp_f32_e32 v52, v52
	s_nop 0
	v_fma_f32 v52, v52, -2.0, 1.0
	v_add_f32_e32 v52, 1.0, v52
	v_mul_f32_e32 v31, v31, v52
	v_mov_b32_e32 v52, v89
	v_pk_mul_f32 v[52:53], v[20:21], v[52:53]
	v_mul_f32_e32 v31, v31, v118
	v_add_f32_e32 v53, v53, v92
	v_add_f32_e32 v52, v52, v53
	v_mul_f32_e32 v53, 0x3d372713, v52
	v_mul_f32_e32 v53, v52, v53
	v_fma_f32 v53, v52, v53, v52
	v_mul_f32_e32 v53, 0x3f4c422a, v53
	v_add_f32_e32 v53, v53, v53
	v_mul_f32_e32 v53, 0x3fb8aa3b, v53
	v_exp_f32_e32 v53, v53
	v_mul_f32_e32 v52, 0.5, v52
	v_cvt_pk_bf16_f32 v31, v93, v31
	v_add_f32_e32 v53, 1.0, v53
	v_rcp_f32_e32 v53, v53
	s_nop 0
	v_fma_f32 v53, v53, -2.0, 1.0
	v_add_f32_e32 v53, 1.0, v53
	v_mul_f32_e32 v52, v52, v53
	v_mul_f32_e32 v89, v52, v94
	v_lshlrev_b32_e32 v52, 16, v32
	v_fma_f32 v92, v6, v52, v14
	v_add_f32_e32 v92, v97, v92
	v_add_f32_e32 v92, v96, v92
	v_mul_f32_e32 v93, 0x3d372713, v92
	v_mul_f32_e32 v93, v92, v93
	v_fma_f32 v93, v92, v93, v92
	v_mul_f32_e32 v93, 0x3f4c422a, v93
	v_add_f32_e32 v93, v93, v93
	v_mul_f32_e32 v93, 0x3fb8aa3b, v93
	v_exp_f32_e32 v93, v93
	v_mul_f32_e32 v92, 0.5, v92
	v_lshlrev_b32_e32 v53, 16, v40
	v_fma_f32 v95, v6, v53, v14
	v_add_f32_e32 v93, 1.0, v93
	v_rcp_f32_e32 v93, v93
	s_nop 0
	v_fma_f32 v93, v93, -2.0, 1.0
	v_add_f32_e32 v93, 1.0, v93
	v_mul_f32_e32 v92, v92, v93
	v_mul_f32_e32 v94, v92, v111
	v_mov_b32_e32 v92, v87
	v_mov_b32_e32 v93, v52
	v_pk_mul_f32 v[92:93], v[72:73], v[92:93]
	s_nop 0
	v_add_f32_e32 v87, v93, v95
	v_add_f32_e32 v87, v92, v87
	v_mul_f32_e32 v92, 0x3d372713, v87
	v_mul_f32_e32 v92, v87, v92
	v_fma_f32 v92, v87, v92, v87
	v_mul_f32_e32 v92, 0x3f4c422a, v92
	v_add_f32_e32 v92, v92, v92
	v_mul_f32_e32 v92, 0x3fb8aa3b, v92
	v_exp_f32_e32 v92, v92
	v_mul_f32_e32 v87, 0.5, v87
	v_add_f32_e32 v92, 1.0, v92
	v_rcp_f32_e32 v92, v92
	s_nop 0
	v_fma_f32 v92, v92, -2.0, 1.0
	v_add_f32_e32 v92, 1.0, v92
	v_mul_f32_e32 v87, v87, v92
	v_mul_f32_e32 v92, v87, v86
	v_and_b32_e32 v86, 0xffff0000, v32
	v_fma_f32 v32, v7, v86, v15
	v_add_f32_e32 v32, v61, v32
	v_add_f32_e32 v32, v60, v32
	v_and_b32_e32 v87, 0xffff0000, v40
	v_mul_f32_e32 v40, 0x3d372713, v32
	v_mul_f32_e32 v40, v32, v40
	v_fma_f32 v40, v32, v40, v32
	v_mul_f32_e32 v40, 0x3f4c422a, v40
	v_add_f32_e32 v40, v40, v40
	v_mul_f32_e32 v40, 0x3fb8aa3b, v40
	v_exp_f32_e32 v40, v40
	v_mul_f32_e32 v32, 0.5, v32
	v_mov_b32_e32 v60, v85
	v_mov_b32_e32 v61, v86
	v_add_f32_e32 v40, 1.0, v40
	v_rcp_f32_e32 v40, v40
	v_pk_mul_f32 v[60:61], v[22:23], v[60:61]
	v_fma_f32 v40, v40, -2.0, 1.0
	v_add_f32_e32 v40, 1.0, v40
	v_mul_f32_e32 v32, v32, v40
	v_fma_f32 v40, v7, v87, v15
	v_add_f32_e32 v40, v61, v40
	v_add_f32_e32 v40, v60, v40
	v_mul_f32_e32 v60, 0x3d372713, v40
	v_mul_f32_e32 v60, v40, v60
	v_fma_f32 v60, v40, v60, v40
	v_mul_f32_e32 v60, 0x3f4c422a, v60
	v_add_f32_e32 v60, v60, v60
	v_mul_f32_e32 v60, 0x3fb8aa3b, v60
	v_exp_f32_e32 v60, v60
	v_mul_f32_e32 v40, 0.5, v40
	v_lshlrev_b32_e32 v61, 16, v41
	v_mul_f32_e32 v32, v32, v110
	v_add_f32_e32 v60, 1.0, v60
	v_rcp_f32_e32 v60, v60
	v_cvt_pk_bf16_f32 v32, v94, v32
	v_and_b32_e32 v41, 0xffff0000, v41
	v_fma_f32 v60, v60, -2.0, 1.0
	v_add_f32_e32 v60, 1.0, v60
	v_mul_f32_e32 v40, v40, v60
	v_lshlrev_b32_e32 v60, 16, v33
	v_mul_f32_e32 v85, v40, v90
	v_fma_f32 v40, v8, v60, v16
	v_add_f32_e32 v40, v57, v40
	v_add_f32_e32 v40, v56, v40
	v_mul_f32_e32 v56, 0x3d372713, v40
	v_mul_f32_e32 v56, v40, v56
	v_fma_f32 v56, v40, v56, v40
	v_mul_f32_e32 v56, 0x3f4c422a, v56
	v_add_f32_e32 v56, v56, v56
	v_mul_f32_e32 v56, 0x3fb8aa3b, v56
	v_exp_f32_e32 v56, v56
	v_mul_f32_e32 v40, 0.5, v40
	v_mov_b32_e32 v57, v60
	v_add_f32_e32 v56, 1.0, v56
	v_rcp_f32_e32 v56, v56
	s_nop 0
	v_fma_f32 v56, v56, -2.0, 1.0
	v_add_f32_e32 v56, 1.0, v56
	v_mul_f32_e32 v40, v40, v56
	v_mov_b32_e32 v56, v83
	v_mul_f32_e32 v90, v40, v109
	v_fma_f32 v40, v8, v61, v16
	v_pk_mul_f32 v[56:57], v[70:71], v[56:57]
	s_nop 0
	v_add_f32_e32 v40, v57, v40
	v_add_f32_e32 v40, v56, v40
	v_mul_f32_e32 v56, 0x3d372713, v40
	v_mul_f32_e32 v56, v40, v56
	v_fma_f32 v56, v40, v56, v40
	v_mul_f32_e32 v56, 0x3f4c422a, v56
	v_add_f32_e32 v56, v56, v56
	v_mul_f32_e32 v56, 0x3fb8aa3b, v56
	v_exp_f32_e32 v56, v56
	v_mul_f32_e32 v40, 0.5, v40
	v_add_f32_e32 v56, 1.0, v56
	v_rcp_f32_e32 v56, v56
	s_nop 0
	v_fma_f32 v56, v56, -2.0, 1.0
	v_add_f32_e32 v56, 1.0, v56
	v_mul_f32_e32 v40, v40, v56
	v_mul_f32_e32 v56, v40, v84
	v_and_b32_e32 v40, 0xffff0000, v33
	v_fma_f32 v33, v9, v40, v17
	v_add_f32_e32 v33, v55, v33
	v_add_f32_e32 v33, v54, v33
	v_mul_f32_e32 v54, 0x3d372713, v33
	v_mul_f32_e32 v54, v33, v54
	v_fma_f32 v54, v33, v54, v33
	v_mul_f32_e32 v54, 0x3f4c422a, v54
	v_add_f32_e32 v54, v54, v54
	v_mul_f32_e32 v54, 0x3fb8aa3b, v54
	v_exp_f32_e32 v54, v54
	v_mul_f32_e32 v33, 0.5, v33
	v_add_f32_e32 v54, 1.0, v54
	v_rcp_f32_e32 v54, v54
	s_nop 0
	v_fma_f32 v54, v54, -2.0, 1.0
	v_add_f32_e32 v54, 1.0, v54
	v_mul_f32_e32 v33, v33, v54
	v_mul_f32_e32 v33, v33, v107
	v_cvt_pk_bf16_f32 v33, v90, v33
	global_store_dwordx4 v[48:49], v[30:33], off
	v_add_u32_e32 v48, s35, v105
	v_add_u32_e32 v49, 2, v48
	v_mov_b32_e32 v30, v59
	v_mov_b32_e32 v31, v40
	v_fma_f32 v32, v9, v41, v17
	v_pk_mul_f32 v[30:31], v[24:25], v[30:31]
	v_cmp_lt_i32_e32 vcc, 61, v49
	v_add_f32_e32 v31, v31, v32
	v_add_f32_e32 v30, v30, v31
	v_mul_f32_e32 v31, 0x3d372713, v30
	v_mul_f32_e32 v31, v30, v31
	v_fma_f32 v31, v30, v31, v30
	v_mul_f32_e32 v31, 0x3f4c422a, v31
	v_add_f32_e32 v31, v31, v31
	v_mul_f32_e32 v31, 0x3fb8aa3b, v31
	v_exp_f32_e32 v31, v31
	v_mul_f32_e32 v30, 0.5, v30
	s_and_b64 s[44:45], s[10:11], vcc
	v_cvt_pk_bf16_f32 v32, v92, v85
	v_add_f32_e32 v31, 1.0, v31
	v_rcp_f32_e32 v31, v31
	s_nop 0
	v_fma_f32 v31, v31, -2.0, 1.0
	v_add_f32_e32 v31, 1.0, v31
	v_mul_f32_e32 v30, v30, v31
	v_mul_f32_e32 v33, v30, v58
	v_cvt_pk_bf16_f32 v30, v82, v88
	v_cvt_pk_bf16_f32 v31, v91, v89
	v_cvt_pk_bf16_f32 v33, v56, v33
	global_store_dwordx4 v[44:45], v[30:33], off
	s_and_saveexec_b64 s[22:23], s[44:45]
	s_cbranch_execz .LBB0_699
; __device__ __forceinline__ void phase_ffn_conv(const Params& p, int l, int bid, int nblk) {
;     ...
;                     if (i >= 62 && (rb == 255 || r >= SEQ)) {
;                         float* dst = r < SEQ ? p.out + O_FP + (size_t)(l * 2 + (i - 62)) * 3072 + c8 : p.out + O_FS + (size_t)((l * 8 + ((r - SEQ) >> 6)) * 2 + (i - 62)) * 3072 + c8;
; #pragma unroll
;                         for (int j = 0; j < 8; ++j) dst[j] = u0[j];
;                     }
	s_load_dwordx2 s[44:45], s[0:1], 0xc8
	v_mov_b32_e32 v30, v43
	v_mov_b32_e32 v31, v47
	v_mov_b32_e32 v32, v51
	v_mov_b32_e32 v33, v39
	s_waitcnt lgkmcnt(0)
	v_lshl_add_u64 v[44:45], s[44:45], 0, v[78:79]
	v_add_co_u32_e32 v44, vcc, 0xffffd000, v44
	s_nop 1
	v_addc_co_u32_e32 v45, vcc, -1, v45, vcc
	global_store_dwordx4 v[44:45], v[30:33], off offset:-28
	s_nop 1
	v_mov_b32_e32 v30, v53
	v_mov_b32_e32 v31, v87
	v_mov_b32_e32 v32, v61
	v_mov_b32_e32 v33, v41
	global_store_dwordx4 v[44:45], v[30:33], off offset:-12
